# static priority raise for the two SSD waves that run stage 0 before the chunk barrier (reset at the seam), on top of the epilogue stack
# speedup vs baseline: 1.0083x; 1.0083x over previous
.LBB0_828:
	s_cmp_lt_i32 s92, 5
	s_cselect_b64 s[0:1], -1, 0
	s_cmp_gt_i32 s93, 4
	s_cselect_b64 s[2:3], -1, 0
	s_and_b64 s[0:1], s[0:1], s[2:3]
	s_andn2_b64 vcc, exec, s[0:1]
	s_cbranch_vccnz .LBB0_979
	v_readfirstlane_b32 vcc_lo, v190
	s_nop 3
	s_cmp_lt_u32 vcc_lo, 128
	s_cbranch_scc0 .Lssd_prio_skip
	s_setprio 1
.Lssd_prio_skip:
	s_waitcnt lgkmcnt(0)
	s_mov_b64 s[0:1], s[90:91]
	s_mov_b64 s[0:1], s[88:89]
	v_mov_b32_e32 v150, v190
	s_cmpk_gt_i32 s97, 0x1ff
	s_cbranch_scc1 .LBB0_925
	v_readlane_b32 s0, v254, 35
	v_readlane_b32 s14, v254, 49
	v_readlane_b32 s15, v254, 50
	s_add_u32 s46, s14, 0x12700000
	v_readlane_b32 s6, v254, 41
	s_addc_u32 s47, s15, 0
	v_readlane_b32 s7, v254, 42
	s_add_u32 s6, s14, 0x22b00000
	v_readlane_b32 s8, v254, 43
	s_addc_u32 s7, s15, 0
	v_readlane_b32 s9, v254, 44
	s_add_u32 s8, s14, 0x3b100000
	s_addc_u32 s9, s15, 0
	v_readlane_b32 s11, v254, 46
	s_add_u32 s48, s14, 0x3ba00000
	v_mbcnt_lo_u32_b32 v160, -1, 0
	s_addc_u32 s49, s15, 0
	s_movk_i32 s50, 0x100
	v_mov_b32_e32 v1, 0
	s_mov_b32 s11, 0
	s_movk_i32 s51, 0x7f
	s_movk_i32 s52, 0x180
	s_movk_i32 s53, 0x880
	s_movk_i32 s54, 0x3000
	s_mov_b32 s55, 0x9000
	s_movk_i32 s56, 0xc00
	s_movk_i32 s57, 0x1000
	s_mov_b32 s58, 0x41a00000
	s_movk_i32 s59, 0x50
	s_add_i32 s60, 0, 0x10c00
	s_movk_i32 s61, 0x210
	s_movk_i32 s62, 0x110
	s_movk_i32 s63, 0x840
	s_movk_i32 s64, 0x600
	s_mov_b32 s65, 0x12400000
	s_movk_i32 s66, 0x3ff
	v_mov_b32_e32 v151, 0x880
	v_mov_b32_e32 v152, 0x700
	v_mov_b32_e32 v153, 0xffffdc00
	v_mov_b32_e32 v154, 0xffffe800
	v_mov_b32_e32 v155, 0xfffff400
	v_mov_b32_e32 v156, 0x2400
	v_mov_b32_e32 v157, 0x3000
	v_mov_b32_e32 v158, 0x3c00
	v_mov_b32_e32 v159, 0x4800
	v_mbcnt_hi_u32_b32 v161, -1, v160
	v_mov_b32_e32 v162, 0xfffffe80
	v_mov_b32_e32 v163, 0xffffff00
	v_mov_b32_e32 v164, 0x2200
	v_mov_b32_e32 v165, 0x15c00
	v_mov_b32_e32 v166, 0x16800
	v_mov_b32_e32 v167, 0x17400
	v_mov_b32_e32 v168, 0x18000
	v_mov_b32_e32 v169, 0x18c00
	v_mov_b32_e32 v170, 0x19800
	v_mov_b32_e32 v171, 0x1a400
	v_mov_b32_e32 v172, 0x1b000
	v_mov_b32_e32 v173, 0x1bc00
	v_mov_b32_e32 v174, 0x1c800
	v_mov_b32_e32 v175, 0x1d400
	s_mov_b32 s67, s97
	v_readlane_b32 s1, v254, 36
	v_readlane_b32 s2, v254, 37
	v_readlane_b32 s3, v254, 38
	v_readlane_b32 s4, v254, 39
	v_readlane_b32 s5, v254, 40
	v_readlane_b32 s10, v254, 45
	v_readlane_b32 s12, v254, 47
	v_readlane_b32 s13, v254, 48
	s_branch .LBB0_832

.LBB0_925:
	v_readlane_b32 s76, v254, 35
	s_cmp_lt_i32 s93, 6
	v_readlane_b32 s86, v254, 45
	v_readlane_b32 s87, v254, 46
	v_readlane_b32 s88, v254, 47
	v_readlane_b32 s89, v254, 48
	v_readlane_b32 s90, v254, 49
	v_readlane_b32 s91, v254, 50
	v_readlane_b32 s77, v254, 36
	v_readlane_b32 s78, v254, 37
	v_readlane_b32 s79, v254, 38
	v_readlane_b32 s80, v254, 39
	v_readlane_b32 s81, v254, 40
	v_readlane_b32 s82, v254, 41
	v_readlane_b32 s83, v254, 42
	v_readlane_b32 s84, v254, 43
	v_readlane_b32 s85, v254, 44
	s_cbranch_scc1 .LBB0_979
	s_setprio 0
	s_getreg_b32 s2, hwreg(HW_REG_XCC_ID, 0, 4)
	s_waitcnt vmcnt(0)
	v_cmp_eq_u32_e32 vcc, 0, v190
	s_waitcnt vmcnt(0) lgkmcnt(0)
	s_barrier
	s_and_saveexec_b64 s[0:1], vcc
	s_cbranch_execz .LBB0_978
	s_add_i32 s3, 0, 0x25f00
	v_mov_b32_e32 v0, s3
	s_waitcnt vmcnt(0) expcnt(0) lgkmcnt(0)
	ds_read_b32 v2, v0
	s_add_i32 s3, 0, 0x25f04
	v_mov_b32_e32 v0, s3
	ds_read_b32 v0, v0
	s_and_b32 s33, s2, 15
	s_waitcnt lgkmcnt(1)
	v_cmp_ne_u32_e32 vcc, 0, v2
	s_cbranch_vccnz .LBB0_942
	v_readlane_b32 s2, v254, 16
	s_mul_i32 s48, s95, s2
	s_add_u32 s2, s90, 0x310200
	s_addc_u32 s3, s91, 0
	s_add_u32 s4, s90, 0x310400
	s_addc_u32 s5, s91, 0
	s_add_u32 s6, s90, 0x310500
	s_addc_u32 s7, s91, 0
	s_add_u32 s8, s90, 0x310600
	s_addc_u32 s9, s91, 0
	s_add_u32 s10, s90, 0x310700
	s_addc_u32 s11, s91, 0
	s_add_u32 s12, s90, 0x310800
	s_addc_u32 s13, s91, 0
	s_add_u32 s14, s90, 0x310900
	s_addc_u32 s15, s91, 0
	s_add_u32 s16, s90, 0x310a00
	s_addc_u32 s17, s91, 0
	s_add_u32 s20, s90, 0x310b00
	s_addc_u32 s21, s91, 0
	s_add_u32 s22, s90, 0x310c00
	s_addc_u32 s23, s91, 0
	s_add_u32 s24, s90, 0x310d00
	s_addc_u32 s25, s91, 0
	s_add_u32 s26, s90, 0x310e00
	s_addc_u32 s27, s91, 0
	s_add_u32 s30, s90, 0x310f00
	s_addc_u32 s31, s91, 0
	s_add_u32 s34, s90, 0x311000
	s_addc_u32 s35, s91, 0
	s_add_u32 s36, s90, 0x311100
	s_addc_u32 s37, s91, 0
	s_add_u32 s38, s90, 0x311200
	s_addc_u32 s39, s91, 0
	s_add_u32 s40, s90, 0x311300
	s_mul_i32 s48, s48, s94
	s_addc_u32 s41, s91, 0
	s_mov_b32 s49, 1
	v_mov_b32_e32 v16, 0
	s_branch .LBB0_930
